# v_c4 + P1 modulate loop handles two 8-element vectors per iteration (12 loads in flight per lane instead of 6)
# baseline (speedup 1.0000x reference)
; __device__ __forceinline__ int fresh_lane() { int l; asm volatile("v_mbcnt_lo_u32_b32 %0, -1, 0\n\tv_mbcnt_hi_u32_b32 %0, -1, %0" : "=v"(l)); return l; }
; __device__ __forceinline__ unsigned pk2(float lo, float hi) { const f32x2 v = {lo, hi}; const bf16x2_n b = __builtin_convertvector(v, bf16x2_n); return __builtin_bit_cast(unsigned, b); }
; __device__ __forceinline__ float lo_bf(unsigned w) { return __uint_as_float(w << 16); }
; __device__ __forceinline__ float hi_bf(unsigned w) { return __uint_as_float(w & 0xffff0000u); }
; __device__ __forceinline__ void modulate_phase(const float* X, const float* MODl  , int sh_off, int sc_off, bf16* H, bf16* HL, int G, int wave_s) {
;     const size_t nth = (size_t)G * 512;
;     int tid_ = wave_s * 64 + fresh_lane(); asm volatile("" : "+v"(tid_));
;     for (size_t e = (size_t)blockIdx.x * 512 + tid_; e < (size_t)MTOK * DM / 8; e += nth) {
;         const int m = (int)(e >> 8), c8 = (int)(e & 255) * 8, b = m >> 11;
;         const f32x4 x0 = *(const f32x4*)(X + (size_t)m * DM + c8), x1 = *(const f32x4*)(X + (size_t)m * DM + c8 + 4);
;         const float* mb = MODl + (size_t)b * 12288;
;         const f32x4 s0 = *(const f32x4*)(mb + sc_off + c8), s1 = *(const f32x4*)(mb + sc_off + c8 + 4);
;         const f32x4 h0 = *(const f32x4*)(mb + sh_off + c8), h1 = *(const f32x4*)(mb + sh_off + c8 + 4);
;         const f32x4 o0 = x0 * (1.0f + s0) + h0, o1 = x1 * (1.0f + s1) + h1;
;         v4u w; if (HF_A == 1) { w.x = pk2h(o0.x, o0.y); w.y = pk2h(o0.z, o0.w); w.z = pk2h(o1.x, o1.y); w.w = pk2h(o1.z, o1.w); } else { w.x = pk2(o0.x, o0.y); w.y = pk2(o0.z, o0.w); w.z = pk2(o1.x, o1.y); w.w = pk2(o1.z, o1.w); }
;         if (HF_A == 2) { v4u l; l.x = pk2(o0.x - lo_bf(w.x), o0.y - hi_bf(w.x)); l.y = pk2(o0.z - lo_bf(w.y), o0.w - hi_bf(w.y)); l.z = pk2(o1.x - lo_bf(w.z), o1.y - hi_bf(w.z)); l.w = pk2(o1.z - lo_bf(w.w), o1.w - hi_bf(w.w)); *(v4u*)(HL + (size_t)m * DM + c8) = l; }
;         *(v4u*)(H + (size_t)m * DM + c8) = w;
;     }
; }
.LBB0_439:
	v_readlane_b32 s2, v253, 0
	s_and_b32 s89, s38, 0xffffffc0
	v_readlane_b32 s3, v253, 1
	s_barrier
	v_mbcnt_lo_u32_b32 v0, -1, 0
	v_mbcnt_hi_u32_b32 v0, -1, v0
	s_mov_b32 s3, 0
	v_add_u32_e32 v2, s89, v0
	v_writelane_b32 v253, s2, 0
	s_lshl_b64 s[10:11], s[2:3], 9
	v_ashrrev_i32_e32 v3, 31, v2
	v_lshl_add_u64 v[0:1], s[10:11], 0, v[2:3]
	s_mov_b64 s[10:11], 0x200000
	v_writelane_b32 v253, s3, 1
	v_cmp_gt_u64_e32 vcc, s[10:11], v[0:1]
	s_and_saveexec_b64 s[10:11], vcc
	s_cbranch_execz .LBB0_442
	s_load_dwordx2 s[6:7], s[6:7], 0x0
	s_add_u32 s16, s8, 0x30600000
	s_addc_u32 s17, s9, 0
	v_readlane_b32 s2, v253, 0
	s_add_u32 s8, s8, 0x1ce00000
	v_readlane_b32 s3, v253, 1
	s_addc_u32 s9, s9, 0
	s_ashr_i32 s5, s4, 31
	s_lshl_b64 s[14:15], s[2:3], 12
	s_lshl_b64 s[12:13], s[4:5], 9
	v_lshl_add_u64 v[2:3], v[2:3], 3, s[14:15]
	s_lshl_b64 s[4:5], s[4:5], 12
	s_mov_b64 s[14:15], 0
	s_waitcnt vmcnt(0)
	v_mov_b32_e32 v5, 0
	v_mov_b32_e32 v45, 0
	s_mov_b32 s3, 0xc000
	v_mov_b64_e32 v[6:7], s[16:17]
	s_mov_b64 s[16:17], 0x2000
	s_movk_i32 s21, 0x2000
	s_mov_b64 s[18:19], 0x1fffff
.LBB0_441:
	s_waitcnt lgkmcnt(0)
	v_lshl_add_u64 v[40:41], v[0:1], 0, s[12:13]
	v_lshl_add_u64 v[42:43], v[2:3], 0, s[4:5]
	v_and_b32_e32 v39, 0xfff800, v2
	v_and_b32_e32 v38, 0x7f8, v2
	v_alignbit_b32 v8, v1, v0, 19
	v_lshlrev_b32_e32 v4, 2, v39
	v_mad_u64_u32 v[8:9], s[22:23], v8, s3, v[6:7]
	v_lshl_add_u64 v[10:11], s[6:7], 0, v[4:5]
	v_lshlrev_b32_e32 v4, 2, v38
	v_lshl_add_u64 v[32:33], v[8:9], 0, v[4:5]
	v_lshl_add_u64 v[16:17], v[10:11], 0, v[4:5]
	v_add_co_u32_e32 v36, vcc, s21, v32
	global_load_dwordx4 v[8:11], v[16:17], off offset:16
	global_load_dwordx4 v[12:15], v[16:17], off
	v_lshl_add_u64 v[34:35], v[32:33], 0, s[16:17]
	v_addc_co_u32_e32 v37, vcc, 0, v33, vcc
	global_load_dwordx4 v[16:19], v[32:33], off
	global_load_dwordx4 v[20:23], v[36:37], off
	global_load_dwordx4 v[24:27], v[34:35], off offset:16
	global_load_dwordx4 v[28:31], v[32:33], off offset:16
	v_lshlrev_b32_e32 v4, 1, v39
	v_lshl_add_u64 v[32:33], s[8:9], 0, v[4:5]
	v_lshlrev_b32_e32 v4, 1, v38
	v_lshl_add_u64 v[32:33], v[32:33], 0, v[4:5]
	v_and_b32_e32 v79, 0xfff800, v42
	v_and_b32_e32 v78, 0x7f8, v42
	v_alignbit_b32 v48, v41, v40, 19
	v_lshlrev_b32_e32 v44, 2, v79
	v_mad_u64_u32 v[48:49], s[22:23], v48, s3, v[6:7]
	v_lshl_add_u64 v[50:51], s[6:7], 0, v[44:45]
	v_lshlrev_b32_e32 v44, 2, v78
	v_lshl_add_u64 v[72:73], v[48:49], 0, v[44:45]
	v_lshl_add_u64 v[56:57], v[50:51], 0, v[44:45]
	v_add_co_u32_e32 v76, vcc, s21, v72
	global_load_dwordx4 v[48:51], v[56:57], off offset:16
	global_load_dwordx4 v[52:55], v[56:57], off
	v_lshl_add_u64 v[74:75], v[72:73], 0, s[16:17]
	v_addc_co_u32_e32 v77, vcc, 0, v73, vcc
	global_load_dwordx4 v[56:59], v[72:73], off
	global_load_dwordx4 v[60:63], v[76:77], off
	global_load_dwordx4 v[64:67], v[74:75], off offset:16
	global_load_dwordx4 v[68:71], v[72:73], off offset:16
	v_lshlrev_b32_e32 v44, 1, v79
	v_lshl_add_u64 v[72:73], s[8:9], 0, v[44:45]
	v_lshlrev_b32_e32 v44, 1, v78
	v_lshl_add_u64 v[72:73], v[72:73], 0, v[44:45]
	v_lshl_add_u64 v[0:1], v[40:41], 0, s[12:13]
	v_lshl_add_u64 v[2:3], v[42:43], 0, s[4:5]
	v_cmp_lt_u64_e32 vcc, s[18:19], v[0:1]
	s_or_b64 s[14:15], vcc, s[14:15]
	s_waitcnt vmcnt(6)
	v_pk_add_f32 v[22:23], v[22:23], 1.0 op_sel_hi:[1,0]
	v_pk_add_f32 v[20:21], v[20:21], 1.0 op_sel_hi:[1,0]
	v_pk_add_f32 v[26:27], v[26:27], 1.0 op_sel_hi:[1,0]
	v_pk_add_f32 v[24:25], v[24:25], 1.0 op_sel_hi:[1,0]
	v_pk_fma_f32 v[14:15], v[14:15], v[22:23], v[18:19]
	v_pk_fma_f32 v[12:13], v[12:13], v[20:21], v[16:17]
	v_pk_fma_f32 v[16:17], v[10:11], v[26:27], v[30:31]
	v_pk_fma_f32 v[10:11], v[8:9], v[24:25], v[28:29]
	v_cvt_pk_bf16_f32 v8, v12, v13
	v_cvt_pk_bf16_f32 v9, v14, v15
	v_cvt_pk_bf16_f32 v10, v10, v11
	v_cvt_pk_bf16_f32 v11, v16, v17
	global_store_dwordx4 v[32:33], v[8:11], off
	s_waitcnt vmcnt(1)
	v_pk_add_f32 v[62:63], v[62:63], 1.0 op_sel_hi:[1,0]
	v_pk_add_f32 v[60:61], v[60:61], 1.0 op_sel_hi:[1,0]
	v_pk_add_f32 v[66:67], v[66:67], 1.0 op_sel_hi:[1,0]
	v_pk_add_f32 v[64:65], v[64:65], 1.0 op_sel_hi:[1,0]
	v_pk_fma_f32 v[54:55], v[54:55], v[62:63], v[58:59]
	v_pk_fma_f32 v[52:53], v[52:53], v[60:61], v[56:57]
	v_pk_fma_f32 v[56:57], v[50:51], v[66:67], v[70:71]
	v_pk_fma_f32 v[50:51], v[48:49], v[64:65], v[68:69]
	v_cvt_pk_bf16_f32 v48, v52, v53
	v_cvt_pk_bf16_f32 v49, v54, v55
	v_cvt_pk_bf16_f32 v50, v50, v51
	v_cvt_pk_bf16_f32 v51, v56, v57
	global_store_dwordx4 v[72:73], v[48:51], off
	s_andn2_b64 exec, exec, s[14:15]
	s_cbranch_execnz .LBB0_441
